# v51 + first-barrier census: 16 serialized counter loads issued back-to-back under one wait
# speedup vs baseline: 1.1009x; 1.0064x over previous
; __device__ __forceinline__ unsigned xb_ld(unsigned* p) { return __hip_atomic_load(p, __ATOMIC_RELAXED, __HIP_MEMORY_SCOPE_AGENT); }
; __device__ __forceinline__ void xcd_barrier_complete(unsigned* bar, unsigned x, unsigned G, unsigned& nloc, unsigned& nx) {
;   unsigned sum, cnt, mine, sp = 0u;
;   for (;;) {
;     sum = 0u; cnt = 0u; mine = 0u;
; #pragma unroll
;     for (unsigned j = 0; j < 16; ++j) { const unsigned c = xb_ld(&bar[XB_XCNT(j)]); sum += c; cnt += (c > 0u) ? 1u : 0u; mine = (j == x) ? c : mine; }
;     if (sum == G) break;
;     __builtin_amdgcn_s_sleep(1);
;     if ((++sp & 255u) == 0u) { if (xb_ld(&bar[XB_TMO])) break; if (sp > XB_SPIN_CAP) { atomicAdd(&bar[XB_TMO], 1u); break; } }
;   }
;   nloc = mine > 0u ? mine : 1u; nx = cnt > 0u ? cnt : 1u;
; }
.LBB0_36:
	v_readlane_b32 s24, v252, 9
	v_readlane_b32 s25, v252, 10
	s_mov_b64 s[36:37], -1
	s_mov_b64 s[38:39], -1
	s_nop 2
	global_load_dword v0, v3, s[24:25] sc1
	v_readlane_b32 s24, v252, 11
	v_readlane_b32 s25, v252, 12
	s_nop 4
	global_load_dword v1, v3, s[24:25] sc1
	v_readlane_b32 s24, v252, 13
	v_readlane_b32 s25, v252, 14
	s_nop 4
	global_load_dword v2, v3, s[24:25] sc1
	v_readlane_b32 s24, v252, 15
	v_readlane_b32 s25, v252, 16
	s_nop 4
	global_load_dword v4, v3, s[24:25] sc1
	v_readlane_b32 s24, v252, 17
	v_readlane_b32 s25, v252, 18
	s_nop 4
	global_load_dword v5, v3, s[24:25] sc1
	v_readlane_b32 s24, v252, 19
	v_readlane_b32 s25, v252, 20
	s_nop 4
	global_load_dword v6, v3, s[24:25] sc1
	v_readlane_b32 s24, v252, 21
	v_readlane_b32 s25, v252, 22
	s_nop 4
	global_load_dword v7, v3, s[24:25] sc1
	v_readlane_b32 s24, v252, 23
	v_readlane_b32 s25, v252, 24
	s_nop 4
	global_load_dword v8, v3, s[24:25] sc1
	v_readlane_b32 s24, v252, 25
	v_readlane_b32 s25, v252, 26
	s_nop 4
	global_load_dword v9, v3, s[24:25] sc1
	v_readlane_b32 s24, v252, 27
	v_readlane_b32 s25, v252, 28
	s_nop 4
	global_load_dword v10, v3, s[24:25] sc1
	v_readlane_b32 s24, v252, 29
	v_readlane_b32 s25, v252, 30
	s_nop 4
	global_load_dword v11, v3, s[24:25] sc1
	v_readlane_b32 s24, v252, 31
	v_readlane_b32 s25, v252, 32
	s_nop 4
	global_load_dword v12, v3, s[24:25] sc1
	v_readlane_b32 s24, v252, 33
	v_readlane_b32 s25, v252, 34
	s_nop 4
	global_load_dword v13, v3, s[24:25] sc1
	v_readlane_b32 s24, v252, 35
	v_readlane_b32 s25, v252, 36
	s_nop 4
	global_load_dword v14, v3, s[24:25] sc1
	v_readlane_b32 s24, v252, 37
	v_readlane_b32 s25, v252, 38
	s_nop 4
	global_load_dword v15, v3, s[24:25] sc1
	v_readlane_b32 s24, v252, 39
	v_readlane_b32 s25, v252, 40
	s_nop 4
	global_load_dword v16, v3, s[24:25] sc1
	s_waitcnt vmcnt(0)
	v_add_u32_e32 v17, v1, v0
	v_add_u32_e32 v17, v17, v2
	v_add_u32_e32 v17, v17, v4
	v_add_u32_e32 v17, v17, v5
	v_add_u32_e32 v17, v17, v6
	v_add_u32_e32 v17, v17, v7
	v_add_u32_e32 v17, v17, v8
	v_add_u32_e32 v17, v17, v9
	v_add_u32_e32 v17, v17, v10
	v_add_u32_e32 v17, v17, v11
	v_add_u32_e32 v17, v17, v12
	v_add_u32_e32 v17, v17, v13
	v_add_u32_e32 v17, v17, v14
	v_add_u32_e32 v17, v17, v15
	v_add_u32_e32 v17, v17, v16
	v_cmp_eq_u32_e32 vcc, s0, v17
	s_cbranch_vccnz .LBB0_35
	s_and_b32 s24, s23, 0xff
	s_cmp_eq_u32 s24, 0
	s_mov_b64 s[40:41], -1
	s_sleep 1
	s_cbranch_scc1 .LBB0_40
	s_and_b64 vcc, exec, s[40:41]
	s_cbranch_vccz .LBB0_35
